# attention step: exit test folded into the band-skip test, V read base computed before the step barrier, scalar pointer math fills the m0 wait states (3 s_nop and ~6 scalar ops fewer per step)
# baseline (speedup 1.0000x reference)
.Lat_nomask_230:
	v_max3_f32 v2, v96, v97, v112
	v_max3_f32 v3, v98, v99, v113
	v_max3_f32 v2, v2, v114, v115
	v_max3_f32 v2, v2, v100, v101
	v_max3_f32 v3, v3, v102, v103
	v_max3_f32 v2, v2, v116, v117
	v_max3_f32 v3, v3, v118, v119
	v_max3_f32 v2, v2, v104, v105
	v_max3_f32 v3, v3, v106, v107
	v_max3_f32 v2, v2, v120, v121
	v_max3_f32 v3, v3, v122, v123
	v_max3_f32 v2, v2, v108, v109
	v_max3_f32 v3, v3, v110, v111
	v_max3_f32 v2, v2, v124, v125
	v_max3_f32 v3, v3, v126, v127
	v_max_f32_e32 v2, v2, v3
	v_mov_b32_e32 v3, v2
	s_nop 1
	v_permlane32_swap_b32_e32 v2, v3
	v_max_f32_e32 v2, v2, v3
	v_mov_b32_e32 v4, v2
	s_mov_b64 s[68:69], 0
	v_add_f32_e32 v248, v248, v4
	v_sub_f32_e32 v96, v96, v4
	v_sub_f32_e32 v97, v97, v4
	v_sub_f32_e32 v98, v98, v4
	v_sub_f32_e32 v99, v99, v4
	v_sub_f32_e32 v100, v100, v4
	v_sub_f32_e32 v101, v101, v4
	v_sub_f32_e32 v102, v102, v4
	v_sub_f32_e32 v103, v103, v4
	v_sub_f32_e32 v104, v104, v4
	v_sub_f32_e32 v105, v105, v4
	v_sub_f32_e32 v106, v106, v4
	v_sub_f32_e32 v107, v107, v4
	v_sub_f32_e32 v108, v108, v4
	v_sub_f32_e32 v109, v109, v4
	v_sub_f32_e32 v110, v110, v4
	v_sub_f32_e32 v111, v111, v4
	v_sub_f32_e32 v112, v112, v4
	v_sub_f32_e32 v113, v113, v4
	v_sub_f32_e32 v114, v114, v4
	v_sub_f32_e32 v115, v115, v4
	v_sub_f32_e32 v116, v116, v4
	v_sub_f32_e32 v117, v117, v4
	v_sub_f32_e32 v118, v118, v4
	v_sub_f32_e32 v119, v119, v4
	v_sub_f32_e32 v120, v120, v4
	v_sub_f32_e32 v121, v121, v4
	v_sub_f32_e32 v122, v122, v4
	v_sub_f32_e32 v123, v123, v4
	v_sub_f32_e32 v124, v124, v4
	v_sub_f32_e32 v125, v125, v4
	v_sub_f32_e32 v126, v126, v4
	v_sub_f32_e32 v127, v127, v4
	v_xor_b32_e32 v5, 0x80000000, v248
	v_mov_b32_e32 v160, v5
	v_mov_b32_e32 v161, v5
	v_mov_b32_e32 v162, v5
	v_mov_b32_e32 v163, v5
	v_mov_b32_e32 v164, v5
	v_mov_b32_e32 v165, v5
	v_mov_b32_e32 v166, v5
	v_mov_b32_e32 v167, v5
	v_mov_b32_e32 v168, v5
	v_mov_b32_e32 v169, v5
	v_mov_b32_e32 v170, v5
	v_mov_b32_e32 v171, v5
	v_mov_b32_e32 v172, v5
	v_mov_b32_e32 v173, v5
	v_mov_b32_e32 v174, v5
	v_mov_b32_e32 v175, v5
	v_exp_f32_e32 v96, v96
	v_exp_f32_e32 v97, v97
	v_exp_f32_e32 v98, v98
	v_exp_f32_e32 v99, v99
	v_exp_f32_e32 v100, v100
	v_exp_f32_e32 v101, v101
	v_exp_f32_e32 v102, v102
	v_exp_f32_e32 v103, v103
	v_exp_f32_e32 v104, v104
	v_exp_f32_e32 v105, v105
	v_exp_f32_e32 v106, v106
	v_exp_f32_e32 v107, v107
	v_exp_f32_e32 v108, v108
	v_exp_f32_e32 v109, v109
	v_exp_f32_e32 v110, v110
	v_exp_f32_e32 v111, v111
	v_exp_f32_e32 v112, v112
	v_exp_f32_e32 v113, v113
	v_exp_f32_e32 v114, v114
	v_exp_f32_e32 v115, v115
	v_exp_f32_e32 v116, v116
	v_exp_f32_e32 v117, v117
	v_exp_f32_e32 v118, v118
	v_exp_f32_e32 v119, v119
	v_exp_f32_e32 v120, v120
	v_exp_f32_e32 v121, v121
	v_exp_f32_e32 v122, v122
	v_exp_f32_e32 v123, v123
	v_exp_f32_e32 v124, v124
	v_exp_f32_e32 v125, v125
	v_exp_f32_e32 v126, v126
	v_exp_f32_e32 v127, v127
	s_waitcnt vmcnt(0) lgkmcnt(0)
	s_barrier
	s_add_i32 m0, s57, s70
	s_nop 0
	global_load_lds_dwordx4 v238, s[74:75]
	s_add_u32 s74, s74, 0x10000
	s_addc_u32 s75, s75, 0
	s_lshl_b32 s60, s58, 1
	s_add_i32 s60, s60, s71
	s_mov_b32 m0, s60
	s_nop 0
	global_load_lds_dwordx4 v239, s[76:77]
	s_add_u32 s62, s76, 0x80
	s_addc_u32 s63, s77, 0
	s_add_i32 m0, s60, 0x2000
	s_nop 0
	global_load_lds_dwordx4 v239, s[62:63]
	s_add_u32 s76, s76, 0x10000
	s_addc_u32 s77, s77, 0
	s_mov_b32 s67, s56
	s_mov_b32 s56, s57
	s_mov_b32 s57, s58
	s_mov_b32 s58, s67
	v_add_u32_e32 v250, s57, v244
	ds_read_b128 v[208:211], v250
	ds_read_b128 v[212:215], v250 offset:512
	ds_read_b128 v[216:219], v250 offset:2048
	ds_read_b128 v[220:223], v250 offset:2560
	ds_read_b128 v[224:227], v250 offset:4096
	ds_read_b128 v[228:231], v250 offset:4608
	ds_read_b128 v[232:235], v250 offset:6144
	ds_read_b128 v[240:243], v250 offset:6656
	s_lshl_b32 s60, s56, 1
	v_add_u32_e32 v250, s60, v245
	s_mov_b32 s46, 1
	s_waitcnt vmcnt(3) lgkmcnt(0)
	s_barrier
.Lat_loop:
	s_cmp_ge_u32 s46, s78
	s_cbranch_scc1 .Lat_lite_445
	v_mfma_f32_32x32x16_bf16 v[128:143], v[208:211], v[16:19], v[160:175]
	v_add_f32_e32 v247, v247, v96
	v_add_f32_e32 v247, v247, v97
	v_add_f32_e32 v247, v247, v98
	v_add_f32_e32 v247, v247, v99
	v_cvt_pk_bf16_f32 v176, v96, v97
	v_cvt_pk_bf16_f32 v177, v98, v99
	v_mfma_f32_32x32x16_bf16 v[144:159], v[212:215], v[16:19], v[160:175]
	v_add_f32_e32 v247, v247, v100
	v_add_f32_e32 v247, v247, v101
	v_add_f32_e32 v247, v247, v102
	v_add_f32_e32 v247, v247, v103
	v_cvt_pk_bf16_f32 v178, v100, v101
	v_cvt_pk_bf16_f32 v179, v102, v103
	v_mfma_f32_32x32x16_bf16 v[128:143], v[216:219], v[20:23], v[128:143]
	v_add_f32_e32 v247, v247, v104
	v_add_f32_e32 v247, v247, v105
	v_add_f32_e32 v247, v247, v106
	v_add_f32_e32 v247, v247, v107
	v_cvt_pk_bf16_f32 v180, v104, v105
	v_cvt_pk_bf16_f32 v181, v106, v107
	v_mfma_f32_32x32x16_bf16 v[144:159], v[220:223], v[20:23], v[144:159]
	v_add_f32_e32 v247, v247, v108
	v_add_f32_e32 v247, v247, v109
	v_add_f32_e32 v247, v247, v110
	v_add_f32_e32 v247, v247, v111
	v_cvt_pk_bf16_f32 v182, v108, v109
	v_cvt_pk_bf16_f32 v183, v110, v111
	v_mfma_f32_32x32x16_bf16 v[128:143], v[224:227], v[24:27], v[128:143]
	v_add_f32_e32 v247, v247, v112
	v_add_f32_e32 v247, v247, v113
	v_add_f32_e32 v247, v247, v114
	v_add_f32_e32 v247, v247, v115
	v_cvt_pk_bf16_f32 v184, v112, v113
	v_cvt_pk_bf16_f32 v185, v114, v115
	v_mfma_f32_32x32x16_bf16 v[144:159], v[228:231], v[24:27], v[144:159]
	v_add_f32_e32 v247, v247, v116
	v_add_f32_e32 v247, v247, v117
	v_add_f32_e32 v247, v247, v118
	v_add_f32_e32 v247, v247, v119
	v_cvt_pk_bf16_f32 v186, v116, v117
	v_cvt_pk_bf16_f32 v187, v118, v119
	v_mfma_f32_32x32x16_bf16 v[128:143], v[232:235], v[28:31], v[128:143]
	v_add_f32_e32 v247, v247, v120
	v_add_f32_e32 v247, v247, v121
	v_add_f32_e32 v247, v247, v122
	v_add_f32_e32 v247, v247, v123
	v_cvt_pk_bf16_f32 v188, v120, v121
	v_cvt_pk_bf16_f32 v189, v122, v123
	ds_read_b64_tr_b16 v[192:193], v250 offset:0
	ds_read_b64_tr_b16 v[194:195], v250 offset:512
	v_mfma_f32_32x32x16_bf16 v[144:159], v[240:243], v[28:31], v[144:159]
	v_add_f32_e32 v247, v247, v124
	v_add_f32_e32 v247, v247, v125
	v_add_f32_e32 v247, v247, v126
	v_add_f32_e32 v247, v247, v127
	v_cvt_pk_bf16_f32 v190, v124, v125
	v_cvt_pk_bf16_f32 v191, v126, v127
	ds_read_b64_tr_b16 v[196:197], v250 offset:4096
	ds_read_b64_tr_b16 v[198:199], v250 offset:4608
	s_add_i32 m0, s57, s70
	s_lshl_b32 s60, s58, 1
	global_load_lds_dwordx4 v238, s[74:75]
	s_add_i32 s60, s60, s71
	s_mov_b32 m0, s60
	s_add_u32 s62, s76, 0x80
	s_addc_u32 s63, s77, 0
	global_load_lds_dwordx4 v239, s[76:77]
	s_add_i32 m0, s60, 0x2000
	s_add_u32 s74, s74, 0x10000
	s_addc_u32 s75, s75, 0
	global_load_lds_dwordx4 v239, s[62:63]
	s_add_u32 s76, s76, 0x10000
	s_addc_u32 s77, s77, 0
	s_cmp_lg_u32 s46, s79
	s_cbranch_scc1 .Lat_nomask_521
	s_sub_u32 s60, s46, s72
	s_lshl_b32 s60, s60, 6
	v_lshl_add_u32 v0, v252, 2, s60
	v_sub_u32_e32 v0, v246, v0
	v_mov_b32_e32 v1, 0xff800000
	v_cmp_gt_i32_e64 s[60:61], 0, v0
	v_cmp_gt_i32_e64 s[62:63], 32, v0
	v_cmp_gt_i32_e64 s[64:65], 1, v0
	v_cmp_gt_i32_e64 s[66:67], 33, v0
	v_cndmask_b32_e64 v128, v128, v1, s[60:61]
	v_cmp_gt_i32_e64 s[60:61], 2, v0
	v_cndmask_b32_e64 v144, v144, v1, s[62:63]
	v_cmp_gt_i32_e64 s[62:63], 34, v0
	v_cndmask_b32_e64 v129, v129, v1, s[64:65]
	v_cmp_gt_i32_e64 s[64:65], 3, v0
	v_cndmask_b32_e64 v145, v145, v1, s[66:67]
	v_cmp_gt_i32_e64 s[66:67], 35, v0
	v_cndmask_b32_e64 v130, v130, v1, s[60:61]
	v_cmp_gt_i32_e64 s[60:61], 8, v0
	v_cndmask_b32_e64 v146, v146, v1, s[62:63]
	v_cmp_gt_i32_e64 s[62:63], 40, v0
	v_cndmask_b32_e64 v131, v131, v1, s[64:65]
	v_cmp_gt_i32_e64 s[64:65], 9, v0
	v_cndmask_b32_e64 v147, v147, v1, s[66:67]
	v_cmp_gt_i32_e64 s[66:67], 41, v0
	v_cndmask_b32_e64 v132, v132, v1, s[60:61]
	v_cmp_gt_i32_e64 s[60:61], 10, v0
	v_cndmask_b32_e64 v148, v148, v1, s[62:63]
	v_cmp_gt_i32_e64 s[62:63], 42, v0
	v_cndmask_b32_e64 v133, v133, v1, s[64:65]
	v_cmp_gt_i32_e64 s[64:65], 11, v0
	v_cndmask_b32_e64 v149, v149, v1, s[66:67]
	v_cmp_gt_i32_e64 s[66:67], 43, v0
	v_cndmask_b32_e64 v134, v134, v1, s[60:61]
	v_cmp_gt_i32_e64 s[60:61], 16, v0
	v_cndmask_b32_e64 v150, v150, v1, s[62:63]
	v_cmp_gt_i32_e64 s[62:63], 48, v0
	v_cndmask_b32_e64 v135, v135, v1, s[64:65]
	v_cmp_gt_i32_e64 s[64:65], 17, v0
	v_cndmask_b32_e64 v151, v151, v1, s[66:67]
	v_cmp_gt_i32_e64 s[66:67], 49, v0
	v_cndmask_b32_e64 v136, v136, v1, s[60:61]
	v_cmp_gt_i32_e64 s[60:61], 18, v0
	v_cndmask_b32_e64 v152, v152, v1, s[62:63]
	v_cmp_gt_i32_e64 s[62:63], 50, v0
	v_cndmask_b32_e64 v137, v137, v1, s[64:65]
	v_cmp_gt_i32_e64 s[64:65], 19, v0
	v_cndmask_b32_e64 v153, v153, v1, s[66:67]
	v_cmp_gt_i32_e64 s[66:67], 51, v0
	v_cndmask_b32_e64 v138, v138, v1, s[60:61]
	v_cmp_gt_i32_e64 s[60:61], 24, v0
	v_cndmask_b32_e64 v154, v154, v1, s[62:63]
	v_cmp_gt_i32_e64 s[62:63], 56, v0
	v_cndmask_b32_e64 v139, v139, v1, s[64:65]
	v_cmp_gt_i32_e64 s[64:65], 25, v0
	v_cndmask_b32_e64 v155, v155, v1, s[66:67]
	v_cmp_gt_i32_e64 s[66:67], 57, v0
	v_cndmask_b32_e64 v140, v140, v1, s[60:61]
	v_cmp_gt_i32_e64 s[60:61], 26, v0
	v_cndmask_b32_e64 v156, v156, v1, s[62:63]
	v_cmp_gt_i32_e64 s[62:63], 58, v0
	v_cndmask_b32_e64 v141, v141, v1, s[64:65]
	v_cmp_gt_i32_e64 s[64:65], 27, v0
	v_cndmask_b32_e64 v157, v157, v1, s[66:67]
	v_cmp_gt_i32_e64 s[66:67], 59, v0
	v_cndmask_b32_e64 v142, v142, v1, s[60:61]
	s_nop 1
	v_cndmask_b32_e64 v158, v158, v1, s[62:63]
	v_cndmask_b32_e64 v143, v143, v1, s[64:65]
	v_cndmask_b32_e64 v159, v159, v1, s[66:67]

.Lat_noresc_445:
	v_add_u32_e32 v3, s58, v244
	ds_read_b64_tr_b16 v[192:193], v250 offset:2048
	ds_read_b64_tr_b16 v[194:195], v250 offset:2560
	ds_read_b64_tr_b16 v[196:197], v250 offset:6144
	ds_read_b64_tr_b16 v[198:199], v250 offset:6656
	s_waitcnt lgkmcnt(4)
	v_mfma_f32_32x32x16_bf16 v[64:79], v[180:183], v[200:203], v[64:79]
	v_exp_f32_e32 v128, v128
	v_exp_f32_e32 v129, v129
	v_exp_f32_e32 v130, v130
	ds_read_b128 v[208:211], v3
	v_mfma_f32_32x32x16_bf16 v[80:95], v[180:183], v[204:207], v[80:95]
	v_exp_f32_e32 v131, v131
	v_exp_f32_e32 v132, v132
	v_exp_f32_e32 v133, v133
	ds_read_b128 v[212:215], v3 offset:512
	ds_read_b64_tr_b16 v[200:201], v250 offset:10240
	ds_read_b64_tr_b16 v[202:203], v250 offset:10752
	ds_read_b64_tr_b16 v[204:205], v250 offset:14336
	ds_read_b64_tr_b16 v[206:207], v250 offset:14848
	s_waitcnt lgkmcnt(6)
	v_mfma_f32_32x32x16_bf16 v[32:47], v[184:187], v[192:195], v[32:47]
	v_exp_f32_e32 v134, v134
	v_exp_f32_e32 v135, v135
	v_exp_f32_e32 v136, v136
	ds_read_b128 v[216:219], v3 offset:2048
	v_mfma_f32_32x32x16_bf16 v[48:63], v[184:187], v[196:199], v[48:63]
	v_exp_f32_e32 v137, v137
	v_exp_f32_e32 v138, v138
	v_exp_f32_e32 v139, v139
	ds_read_b128 v[220:223], v3 offset:2560
	ds_read_b64_tr_b16 v[192:193], v250 offset:3072
	ds_read_b64_tr_b16 v[194:195], v250 offset:3584
	ds_read_b64_tr_b16 v[196:197], v250 offset:7168
	ds_read_b64_tr_b16 v[198:199], v250 offset:7680
	s_waitcnt lgkmcnt(6)
	v_mfma_f32_32x32x16_bf16 v[64:79], v[184:187], v[200:203], v[64:79]
	v_exp_f32_e32 v140, v140
	v_exp_f32_e32 v141, v141
	v_exp_f32_e32 v142, v142
	ds_read_b128 v[224:227], v3 offset:4096
	v_mfma_f32_32x32x16_bf16 v[80:95], v[184:187], v[204:207], v[80:95]
	v_exp_f32_e32 v143, v143
	v_exp_f32_e32 v144, v144
	v_exp_f32_e32 v145, v145
	ds_read_b128 v[228:231], v3 offset:4608
	ds_read_b64_tr_b16 v[200:201], v250 offset:11264
	ds_read_b64_tr_b16 v[202:203], v250 offset:11776
	ds_read_b64_tr_b16 v[204:205], v250 offset:15360
	ds_read_b64_tr_b16 v[206:207], v250 offset:15872
	s_waitcnt lgkmcnt(6)
	v_mfma_f32_32x32x16_bf16 v[32:47], v[188:191], v[192:195], v[32:47]
	v_exp_f32_e32 v146, v146
	v_exp_f32_e32 v147, v147
	v_exp_f32_e32 v148, v148
	ds_read_b128 v[232:235], v3 offset:6144
	v_mfma_f32_32x32x16_bf16 v[48:63], v[188:191], v[196:199], v[48:63]
	v_exp_f32_e32 v149, v149
	v_exp_f32_e32 v150, v150
	v_exp_f32_e32 v151, v151
	ds_read_b128 v[240:243], v3 offset:6656
	s_waitcnt lgkmcnt(2)
	v_mfma_f32_32x32x16_bf16 v[64:79], v[188:191], v[200:203], v[64:79]
	v_exp_f32_e32 v152, v152
	v_exp_f32_e32 v153, v153
	v_exp_f32_e32 v154, v154
	v_exp_f32_e32 v155, v155
	v_mfma_f32_32x32x16_bf16 v[80:95], v[188:191], v[204:207], v[80:95]
	v_exp_f32_e32 v156, v156
	v_exp_f32_e32 v157, v157
	v_exp_f32_e32 v158, v158
	v_exp_f32_e32 v159, v159
	s_mov_b32 s67, s56
	s_mov_b32 s56, s57
	s_mov_b32 s57, s58
	s_mov_b32 s58, s67
	s_add_u32 s46, s46, 1
	s_lshl_b32 s60, s56, 1
	v_add_u32_e32 v250, s60, v245
	s_waitcnt vmcnt(3) lgkmcnt(0)
	s_barrier
	s_cmp_lg_u64 s[68:69], 0
	s_cbranch_scc0 .Lat_norescO_445
	v_lshl_add_u32 v251, v252, 4, v249
	ds_read_b128 v[0:3], v251 offset:0
	ds_read_b128 v[4:7], v251 offset:32
	ds_read_b128 v[8:11], v251 offset:64
	ds_read_b128 v[12:15], v251 offset:96
	s_nop 7
	s_nop 7
	s_waitcnt lgkmcnt(0)
	v_mul_f32_e32 v32, v32, v0
	v_mul_f32_e32 v33, v33, v1
	v_mul_f32_e32 v34, v34, v2
	v_mul_f32_e32 v35, v35, v3
	v_mul_f32_e32 v36, v36, v4
	v_mul_f32_e32 v37, v37, v5
	v_mul_f32_e32 v38, v38, v6
	v_mul_f32_e32 v39, v39, v7
	v_mul_f32_e32 v40, v40, v8
	v_mul_f32_e32 v41, v41, v9
	v_mul_f32_e32 v42, v42, v10
	v_mul_f32_e32 v43, v43, v11
	v_mul_f32_e32 v44, v44, v12
	v_mul_f32_e32 v45, v45, v13
	v_mul_f32_e32 v46, v46, v14
	v_mul_f32_e32 v47, v47, v15
	v_mul_f32_e32 v48, v48, v0
	v_mul_f32_e32 v49, v49, v1
	v_mul_f32_e32 v50, v50, v2
	v_mul_f32_e32 v51, v51, v3
	v_mul_f32_e32 v52, v52, v4
	v_mul_f32_e32 v53, v53, v5
	v_mul_f32_e32 v54, v54, v6
	v_mul_f32_e32 v55, v55, v7
	v_mul_f32_e32 v56, v56, v8
	v_mul_f32_e32 v57, v57, v9
	v_mul_f32_e32 v58, v58, v10
	v_mul_f32_e32 v59, v59, v11
	v_mul_f32_e32 v60, v60, v12
	v_mul_f32_e32 v61, v61, v13
	v_mul_f32_e32 v62, v62, v14
	v_mul_f32_e32 v63, v63, v15
	v_mul_f32_e32 v64, v64, v0
	v_mul_f32_e32 v65, v65, v1
	v_mul_f32_e32 v66, v66, v2
	v_mul_f32_e32 v67, v67, v3
	v_mul_f32_e32 v68, v68, v4
	v_mul_f32_e32 v69, v69, v5
	v_mul_f32_e32 v70, v70, v6
	v_mul_f32_e32 v71, v71, v7
	v_mul_f32_e32 v72, v72, v8
	v_mul_f32_e32 v73, v73, v9
	v_mul_f32_e32 v74, v74, v10
	v_mul_f32_e32 v75, v75, v11
	v_mul_f32_e32 v76, v76, v12
	v_mul_f32_e32 v77, v77, v13
	v_mul_f32_e32 v78, v78, v14
	v_mul_f32_e32 v79, v79, v15
	v_mul_f32_e32 v80, v80, v0
	v_mul_f32_e32 v81, v81, v1
	v_mul_f32_e32 v82, v82, v2
	v_mul_f32_e32 v83, v83, v3
	v_mul_f32_e32 v84, v84, v4
	v_mul_f32_e32 v85, v85, v5
	v_mul_f32_e32 v86, v86, v6
	v_mul_f32_e32 v87, v87, v7
	v_mul_f32_e32 v88, v88, v8
	v_mul_f32_e32 v89, v89, v9
	v_mul_f32_e32 v90, v90, v10
	v_mul_f32_e32 v91, v91, v11
	v_mul_f32_e32 v92, v92, v12
	v_mul_f32_e32 v93, v93, v13
	v_mul_f32_e32 v94, v94, v14
	v_mul_f32_e32 v95, v95, v15
.Lat_norescO_445:
.Lat_next_445:
	s_cmp_ge_u32 s46, s78
	s_cbranch_scc1 .Lat_lite_859
	v_mfma_f32_32x32x16_bf16 v[96:111], v[208:211], v[16:19], v[160:175]
	v_add_f32_e32 v247, v247, v128
	v_add_f32_e32 v247, v247, v129
	v_add_f32_e32 v247, v247, v130
	v_add_f32_e32 v247, v247, v131
	v_cvt_pk_bf16_f32 v176, v128, v129
	v_cvt_pk_bf16_f32 v177, v130, v131
	v_mfma_f32_32x32x16_bf16 v[112:127], v[212:215], v[16:19], v[160:175]
	v_add_f32_e32 v247, v247, v132
	v_add_f32_e32 v247, v247, v133
	v_add_f32_e32 v247, v247, v134
	v_add_f32_e32 v247, v247, v135
	v_cvt_pk_bf16_f32 v178, v132, v133
	v_cvt_pk_bf16_f32 v179, v134, v135
	v_mfma_f32_32x32x16_bf16 v[96:111], v[216:219], v[20:23], v[96:111]
	v_add_f32_e32 v247, v247, v136
	v_add_f32_e32 v247, v247, v137
	v_add_f32_e32 v247, v247, v138
	v_add_f32_e32 v247, v247, v139
	v_cvt_pk_bf16_f32 v180, v136, v137
	v_cvt_pk_bf16_f32 v181, v138, v139
	v_mfma_f32_32x32x16_bf16 v[112:127], v[220:223], v[20:23], v[112:127]
	v_add_f32_e32 v247, v247, v140
	v_add_f32_e32 v247, v247, v141
	v_add_f32_e32 v247, v247, v142
	v_add_f32_e32 v247, v247, v143
	v_cvt_pk_bf16_f32 v182, v140, v141
	v_cvt_pk_bf16_f32 v183, v142, v143
	v_mfma_f32_32x32x16_bf16 v[96:111], v[224:227], v[24:27], v[96:111]
	v_add_f32_e32 v247, v247, v144
	v_add_f32_e32 v247, v247, v145
	v_add_f32_e32 v247, v247, v146
	v_add_f32_e32 v247, v247, v147
	v_cvt_pk_bf16_f32 v184, v144, v145
	v_cvt_pk_bf16_f32 v185, v146, v147
	v_mfma_f32_32x32x16_bf16 v[112:127], v[228:231], v[24:27], v[112:127]
	v_add_f32_e32 v247, v247, v148
	v_add_f32_e32 v247, v247, v149
	v_add_f32_e32 v247, v247, v150
	v_add_f32_e32 v247, v247, v151
	v_cvt_pk_bf16_f32 v186, v148, v149
	v_cvt_pk_bf16_f32 v187, v150, v151
	v_mfma_f32_32x32x16_bf16 v[96:111], v[232:235], v[28:31], v[96:111]
	v_add_f32_e32 v247, v247, v152
	v_add_f32_e32 v247, v247, v153
	v_add_f32_e32 v247, v247, v154
	v_add_f32_e32 v247, v247, v155
	v_cvt_pk_bf16_f32 v188, v152, v153
	v_cvt_pk_bf16_f32 v189, v154, v155
	ds_read_b64_tr_b16 v[192:193], v250 offset:0
	ds_read_b64_tr_b16 v[194:195], v250 offset:512
	v_mfma_f32_32x32x16_bf16 v[112:127], v[240:243], v[28:31], v[112:127]
	v_add_f32_e32 v247, v247, v156
	v_add_f32_e32 v247, v247, v157
	v_add_f32_e32 v247, v247, v158
	v_add_f32_e32 v247, v247, v159
	v_cvt_pk_bf16_f32 v190, v156, v157
	v_cvt_pk_bf16_f32 v191, v158, v159
	ds_read_b64_tr_b16 v[196:197], v250 offset:4096
	ds_read_b64_tr_b16 v[198:199], v250 offset:4608
	s_add_i32 m0, s57, s70
	s_lshl_b32 s60, s58, 1
	global_load_lds_dwordx4 v238, s[74:75]
	s_add_i32 s60, s60, s71
	s_mov_b32 m0, s60
	s_add_u32 s62, s76, 0x80
	s_addc_u32 s63, s77, 0
	global_load_lds_dwordx4 v239, s[76:77]
	s_add_i32 m0, s60, 0x2000
	s_add_u32 s74, s74, 0x10000
	s_addc_u32 s75, s75, 0
	global_load_lds_dwordx4 v239, s[62:63]
	s_add_u32 s76, s76, 0x10000
	s_addc_u32 s77, s77, 0
	s_cmp_lg_u32 s46, s79
	s_cbranch_scc1 .Lat_nomask_935
	s_sub_u32 s60, s46, s72
	s_lshl_b32 s60, s60, 6
	v_lshl_add_u32 v0, v252, 2, s60
	v_sub_u32_e32 v0, v246, v0
	v_mov_b32_e32 v1, 0xff800000
	v_cmp_gt_i32_e64 s[60:61], 0, v0
	v_cmp_gt_i32_e64 s[62:63], 32, v0
	v_cmp_gt_i32_e64 s[64:65], 1, v0
	v_cmp_gt_i32_e64 s[66:67], 33, v0
	v_cndmask_b32_e64 v96, v96, v1, s[60:61]
	v_cmp_gt_i32_e64 s[60:61], 2, v0
	v_cndmask_b32_e64 v112, v112, v1, s[62:63]
	v_cmp_gt_i32_e64 s[62:63], 34, v0
	v_cndmask_b32_e64 v97, v97, v1, s[64:65]
	v_cmp_gt_i32_e64 s[64:65], 3, v0
	v_cndmask_b32_e64 v113, v113, v1, s[66:67]
	v_cmp_gt_i32_e64 s[66:67], 35, v0
	v_cndmask_b32_e64 v98, v98, v1, s[60:61]
	v_cmp_gt_i32_e64 s[60:61], 8, v0
	v_cndmask_b32_e64 v114, v114, v1, s[62:63]
	v_cmp_gt_i32_e64 s[62:63], 40, v0
	v_cndmask_b32_e64 v99, v99, v1, s[64:65]
	v_cmp_gt_i32_e64 s[64:65], 9, v0
	v_cndmask_b32_e64 v115, v115, v1, s[66:67]
	v_cmp_gt_i32_e64 s[66:67], 41, v0
	v_cndmask_b32_e64 v100, v100, v1, s[60:61]
	v_cmp_gt_i32_e64 s[60:61], 10, v0
	v_cndmask_b32_e64 v116, v116, v1, s[62:63]
	v_cmp_gt_i32_e64 s[62:63], 42, v0
	v_cndmask_b32_e64 v101, v101, v1, s[64:65]
	v_cmp_gt_i32_e64 s[64:65], 11, v0
	v_cndmask_b32_e64 v117, v117, v1, s[66:67]
	v_cmp_gt_i32_e64 s[66:67], 43, v0
	v_cndmask_b32_e64 v102, v102, v1, s[60:61]
	v_cmp_gt_i32_e64 s[60:61], 16, v0
	v_cndmask_b32_e64 v118, v118, v1, s[62:63]
	v_cmp_gt_i32_e64 s[62:63], 48, v0
	v_cndmask_b32_e64 v103, v103, v1, s[64:65]
	v_cmp_gt_i32_e64 s[64:65], 17, v0
	v_cndmask_b32_e64 v119, v119, v1, s[66:67]
	v_cmp_gt_i32_e64 s[66:67], 49, v0
	v_cndmask_b32_e64 v104, v104, v1, s[60:61]
	v_cmp_gt_i32_e64 s[60:61], 18, v0
	v_cndmask_b32_e64 v120, v120, v1, s[62:63]
	v_cmp_gt_i32_e64 s[62:63], 50, v0
	v_cndmask_b32_e64 v105, v105, v1, s[64:65]
	v_cmp_gt_i32_e64 s[64:65], 19, v0
	v_cndmask_b32_e64 v121, v121, v1, s[66:67]
	v_cmp_gt_i32_e64 s[66:67], 51, v0
	v_cndmask_b32_e64 v106, v106, v1, s[60:61]
	v_cmp_gt_i32_e64 s[60:61], 24, v0
	v_cndmask_b32_e64 v122, v122, v1, s[62:63]
	v_cmp_gt_i32_e64 s[62:63], 56, v0
	v_cndmask_b32_e64 v107, v107, v1, s[64:65]
	v_cmp_gt_i32_e64 s[64:65], 25, v0
	v_cndmask_b32_e64 v123, v123, v1, s[66:67]
	v_cmp_gt_i32_e64 s[66:67], 57, v0
	v_cndmask_b32_e64 v108, v108, v1, s[60:61]
	v_cmp_gt_i32_e64 s[60:61], 26, v0
	v_cndmask_b32_e64 v124, v124, v1, s[62:63]
	v_cmp_gt_i32_e64 s[62:63], 58, v0
	v_cndmask_b32_e64 v109, v109, v1, s[64:65]
	v_cmp_gt_i32_e64 s[64:65], 27, v0
	v_cndmask_b32_e64 v125, v125, v1, s[66:67]
	v_cmp_gt_i32_e64 s[66:67], 59, v0
	v_cndmask_b32_e64 v110, v110, v1, s[60:61]
	s_nop 1
	v_cndmask_b32_e64 v126, v126, v1, s[62:63]
	v_cndmask_b32_e64 v111, v111, v1, s[64:65]
	v_cndmask_b32_e64 v127, v127, v1, s[66:67]

.Lat_noresc_859:
	v_add_u32_e32 v3, s58, v244
	ds_read_b64_tr_b16 v[192:193], v250 offset:2048
	ds_read_b64_tr_b16 v[194:195], v250 offset:2560
	ds_read_b64_tr_b16 v[196:197], v250 offset:6144
	ds_read_b64_tr_b16 v[198:199], v250 offset:6656
	s_waitcnt lgkmcnt(4)
	v_mfma_f32_32x32x16_bf16 v[64:79], v[180:183], v[200:203], v[64:79]
	v_exp_f32_e32 v96, v96
	v_exp_f32_e32 v97, v97
	v_exp_f32_e32 v98, v98
	ds_read_b128 v[208:211], v3
	v_mfma_f32_32x32x16_bf16 v[80:95], v[180:183], v[204:207], v[80:95]
	v_exp_f32_e32 v99, v99
	v_exp_f32_e32 v100, v100
	v_exp_f32_e32 v101, v101
	ds_read_b128 v[212:215], v3 offset:512
	ds_read_b64_tr_b16 v[200:201], v250 offset:10240
	ds_read_b64_tr_b16 v[202:203], v250 offset:10752
	ds_read_b64_tr_b16 v[204:205], v250 offset:14336
	ds_read_b64_tr_b16 v[206:207], v250 offset:14848
	s_waitcnt lgkmcnt(6)
	v_mfma_f32_32x32x16_bf16 v[32:47], v[184:187], v[192:195], v[32:47]
	v_exp_f32_e32 v102, v102
	v_exp_f32_e32 v103, v103
	v_exp_f32_e32 v104, v104
	ds_read_b128 v[216:219], v3 offset:2048
	v_mfma_f32_32x32x16_bf16 v[48:63], v[184:187], v[196:199], v[48:63]
	v_exp_f32_e32 v105, v105
	v_exp_f32_e32 v106, v106
	v_exp_f32_e32 v107, v107
	ds_read_b128 v[220:223], v3 offset:2560
	ds_read_b64_tr_b16 v[192:193], v250 offset:3072
	ds_read_b64_tr_b16 v[194:195], v250 offset:3584
	ds_read_b64_tr_b16 v[196:197], v250 offset:7168
	ds_read_b64_tr_b16 v[198:199], v250 offset:7680
	s_waitcnt lgkmcnt(6)
	v_mfma_f32_32x32x16_bf16 v[64:79], v[184:187], v[200:203], v[64:79]
	v_exp_f32_e32 v108, v108
	v_exp_f32_e32 v109, v109
	v_exp_f32_e32 v110, v110
	ds_read_b128 v[224:227], v3 offset:4096
	v_mfma_f32_32x32x16_bf16 v[80:95], v[184:187], v[204:207], v[80:95]
	v_exp_f32_e32 v111, v111
	v_exp_f32_e32 v112, v112
	v_exp_f32_e32 v113, v113
	ds_read_b128 v[228:231], v3 offset:4608
	ds_read_b64_tr_b16 v[200:201], v250 offset:11264
	ds_read_b64_tr_b16 v[202:203], v250 offset:11776
	ds_read_b64_tr_b16 v[204:205], v250 offset:15360
	ds_read_b64_tr_b16 v[206:207], v250 offset:15872
	s_waitcnt lgkmcnt(6)
	v_mfma_f32_32x32x16_bf16 v[32:47], v[188:191], v[192:195], v[32:47]
	v_exp_f32_e32 v114, v114
	v_exp_f32_e32 v115, v115
	v_exp_f32_e32 v116, v116
	ds_read_b128 v[232:235], v3 offset:6144
	v_mfma_f32_32x32x16_bf16 v[48:63], v[188:191], v[196:199], v[48:63]
	v_exp_f32_e32 v117, v117
	v_exp_f32_e32 v118, v118
	v_exp_f32_e32 v119, v119
	ds_read_b128 v[240:243], v3 offset:6656
	s_waitcnt lgkmcnt(2)
	v_mfma_f32_32x32x16_bf16 v[64:79], v[188:191], v[200:203], v[64:79]
	v_exp_f32_e32 v120, v120
	v_exp_f32_e32 v121, v121
	v_exp_f32_e32 v122, v122
	v_exp_f32_e32 v123, v123
	v_mfma_f32_32x32x16_bf16 v[80:95], v[188:191], v[204:207], v[80:95]
	v_exp_f32_e32 v124, v124
	v_exp_f32_e32 v125, v125
	v_exp_f32_e32 v126, v126
	v_exp_f32_e32 v127, v127
	s_mov_b32 s67, s56
	s_mov_b32 s56, s57
	s_mov_b32 s57, s58
	s_mov_b32 s58, s67
	s_add_u32 s46, s46, 1
	s_lshl_b32 s60, s56, 1
	v_add_u32_e32 v250, s60, v245
	s_waitcnt vmcnt(3) lgkmcnt(0)
	s_barrier
	s_cmp_lg_u64 s[68:69], 0
	s_cbranch_scc0 .Lat_norescO_859
	v_lshl_add_u32 v251, v252, 4, v249
	ds_read_b128 v[0:3], v251 offset:0
	ds_read_b128 v[4:7], v251 offset:32
	ds_read_b128 v[8:11], v251 offset:64
	ds_read_b128 v[12:15], v251 offset:96
	s_nop 7
	s_nop 7
	s_waitcnt lgkmcnt(0)
	v_mul_f32_e32 v32, v32, v0
	v_mul_f32_e32 v33, v33, v1
	v_mul_f32_e32 v34, v34, v2
	v_mul_f32_e32 v35, v35, v3
	v_mul_f32_e32 v36, v36, v4
	v_mul_f32_e32 v37, v37, v5
	v_mul_f32_e32 v38, v38, v6
	v_mul_f32_e32 v39, v39, v7
	v_mul_f32_e32 v40, v40, v8
	v_mul_f32_e32 v41, v41, v9
	v_mul_f32_e32 v42, v42, v10
	v_mul_f32_e32 v43, v43, v11
	v_mul_f32_e32 v44, v44, v12
	v_mul_f32_e32 v45, v45, v13
	v_mul_f32_e32 v46, v46, v14
	v_mul_f32_e32 v47, v47, v15
	v_mul_f32_e32 v48, v48, v0
	v_mul_f32_e32 v49, v49, v1
	v_mul_f32_e32 v50, v50, v2
	v_mul_f32_e32 v51, v51, v3
	v_mul_f32_e32 v52, v52, v4
	v_mul_f32_e32 v53, v53, v5
	v_mul_f32_e32 v54, v54, v6
	v_mul_f32_e32 v55, v55, v7
	v_mul_f32_e32 v56, v56, v8
	v_mul_f32_e32 v57, v57, v9
	v_mul_f32_e32 v58, v58, v10
	v_mul_f32_e32 v59, v59, v11
	v_mul_f32_e32 v60, v60, v12
	v_mul_f32_e32 v61, v61, v13
	v_mul_f32_e32 v62, v62, v14
	v_mul_f32_e32 v63, v63, v15
	v_mul_f32_e32 v64, v64, v0
	v_mul_f32_e32 v65, v65, v1
	v_mul_f32_e32 v66, v66, v2
	v_mul_f32_e32 v67, v67, v3
	v_mul_f32_e32 v68, v68, v4
	v_mul_f32_e32 v69, v69, v5
	v_mul_f32_e32 v70, v70, v6
	v_mul_f32_e32 v71, v71, v7
	v_mul_f32_e32 v72, v72, v8
	v_mul_f32_e32 v73, v73, v9
	v_mul_f32_e32 v74, v74, v10
	v_mul_f32_e32 v75, v75, v11
	v_mul_f32_e32 v76, v76, v12
	v_mul_f32_e32 v77, v77, v13
	v_mul_f32_e32 v78, v78, v14
	v_mul_f32_e32 v79, v79, v15
	v_mul_f32_e32 v80, v80, v0
	v_mul_f32_e32 v81, v81, v1
	v_mul_f32_e32 v82, v82, v2
	v_mul_f32_e32 v83, v83, v3
	v_mul_f32_e32 v84, v84, v4
	v_mul_f32_e32 v85, v85, v5
	v_mul_f32_e32 v86, v86, v6
	v_mul_f32_e32 v87, v87, v7
	v_mul_f32_e32 v88, v88, v8
	v_mul_f32_e32 v89, v89, v9
	v_mul_f32_e32 v90, v90, v10
	v_mul_f32_e32 v91, v91, v11
	v_mul_f32_e32 v92, v92, v12
	v_mul_f32_e32 v93, v93, v13
	v_mul_f32_e32 v94, v94, v14
	v_mul_f32_e32 v95, v95, v15
.Lat_norescO_859:
.Lat_next_859:
	s_branch .Lat_loop
	s_branch .Lat_drain
.Lat_lite_445:
	s_cmp_ge_u32 s46, s45
	s_cbranch_scc1 .Lat_drain
	s_cmp_eq_u32 s46, s78
	s_cbranch_scc0 .Lat_lite2_445
	v_add_f32_e32 v247, v247, v96
	v_add_f32_e32 v247, v247, v97
	v_add_f32_e32 v247, v247, v98
	v_add_f32_e32 v247, v247, v99
	v_cvt_pk_bf16_f32 v176, v96, v97
	v_cvt_pk_bf16_f32 v177, v98, v99
	v_add_f32_e32 v247, v247, v100
	v_add_f32_e32 v247, v247, v101
	v_add_f32_e32 v247, v247, v102
	v_add_f32_e32 v247, v247, v103
	v_cvt_pk_bf16_f32 v178, v100, v101
	v_cvt_pk_bf16_f32 v179, v102, v103
	v_add_f32_e32 v247, v247, v104
	v_add_f32_e32 v247, v247, v105
	v_add_f32_e32 v247, v247, v106
	v_add_f32_e32 v247, v247, v107
	v_cvt_pk_bf16_f32 v180, v104, v105
	v_cvt_pk_bf16_f32 v181, v106, v107
	v_add_f32_e32 v247, v247, v108
	v_add_f32_e32 v247, v247, v109
	v_add_f32_e32 v247, v247, v110
	v_add_f32_e32 v247, v247, v111
	v_cvt_pk_bf16_f32 v182, v108, v109
	v_cvt_pk_bf16_f32 v183, v110, v111
	v_add_f32_e32 v247, v247, v112
	v_add_f32_e32 v247, v247, v113
	v_add_f32_e32 v247, v247, v114
	v_add_f32_e32 v247, v247, v115
	v_cvt_pk_bf16_f32 v184, v112, v113
	v_cvt_pk_bf16_f32 v185, v114, v115
	v_add_f32_e32 v247, v247, v116
	v_add_f32_e32 v247, v247, v117
	v_add_f32_e32 v247, v247, v118
	v_add_f32_e32 v247, v247, v119
	v_cvt_pk_bf16_f32 v186, v116, v117
	v_cvt_pk_bf16_f32 v187, v118, v119
	v_add_f32_e32 v247, v247, v120
	v_add_f32_e32 v247, v247, v121
	v_add_f32_e32 v247, v247, v122
	v_add_f32_e32 v247, v247, v123
	v_cvt_pk_bf16_f32 v188, v120, v121
	v_cvt_pk_bf16_f32 v189, v122, v123
	v_add_f32_e32 v247, v247, v124
	v_add_f32_e32 v247, v247, v125
	v_add_f32_e32 v247, v247, v126
	v_add_f32_e32 v247, v247, v127
	v_cvt_pk_bf16_f32 v190, v124, v125
	v_cvt_pk_bf16_f32 v191, v126, v127
	s_lshl_b32 s60, s56, 1
	v_add_u32_e32 v250, s60, v245
	ds_read_b64_tr_b16 v[192:193], v250 offset:0
	ds_read_b64_tr_b16 v[194:195], v250 offset:512
	ds_read_b64_tr_b16 v[196:197], v250 offset:4096
	ds_read_b64_tr_b16 v[198:199], v250 offset:4608
	ds_read_b64_tr_b16 v[200:201], v250 offset:8192
	ds_read_b64_tr_b16 v[202:203], v250 offset:8704
	ds_read_b64_tr_b16 v[204:205], v250 offset:12288
	ds_read_b64_tr_b16 v[206:207], v250 offset:12800
	s_waitcnt lgkmcnt(6)
	v_mfma_f32_32x32x16_bf16 v[32:47], v[176:179], v[192:195], v[32:47]
	ds_read_b64_tr_b16 v[192:193], v250 offset:1024
	ds_read_b64_tr_b16 v[194:195], v250 offset:1536
	s_waitcnt lgkmcnt(6)
	v_mfma_f32_32x32x16_bf16 v[48:63], v[176:179], v[196:199], v[48:63]
	ds_read_b64_tr_b16 v[196:197], v250 offset:5120
	ds_read_b64_tr_b16 v[198:199], v250 offset:5632
	s_waitcnt lgkmcnt(6)
	v_mfma_f32_32x32x16_bf16 v[64:79], v[176:179], v[200:203], v[64:79]
	ds_read_b64_tr_b16 v[200:201], v250 offset:9216
	ds_read_b64_tr_b16 v[202:203], v250 offset:9728
	s_waitcnt lgkmcnt(6)
	v_mfma_f32_32x32x16_bf16 v[80:95], v[176:179], v[204:207], v[80:95]
	ds_read_b64_tr_b16 v[204:205], v250 offset:13312
	ds_read_b64_tr_b16 v[206:207], v250 offset:13824
	s_waitcnt lgkmcnt(6)
	v_mfma_f32_32x32x16_bf16 v[32:47], v[180:183], v[192:195], v[32:47]
	ds_read_b64_tr_b16 v[192:193], v250 offset:2048
	ds_read_b64_tr_b16 v[194:195], v250 offset:2560
	s_waitcnt lgkmcnt(6)
	v_mfma_f32_32x32x16_bf16 v[48:63], v[180:183], v[196:199], v[48:63]
	ds_read_b64_tr_b16 v[196:197], v250 offset:6144
	ds_read_b64_tr_b16 v[198:199], v250 offset:6656
	s_waitcnt lgkmcnt(6)
	v_mfma_f32_32x32x16_bf16 v[64:79], v[180:183], v[200:203], v[64:79]
	ds_read_b64_tr_b16 v[200:201], v250 offset:10240
	ds_read_b64_tr_b16 v[202:203], v250 offset:10752
	s_waitcnt lgkmcnt(6)
	v_mfma_f32_32x32x16_bf16 v[80:95], v[180:183], v[204:207], v[80:95]
	ds_read_b64_tr_b16 v[204:205], v250 offset:14336
	ds_read_b64_tr_b16 v[206:207], v250 offset:14848
	s_waitcnt lgkmcnt(6)
	v_mfma_f32_32x32x16_bf16 v[32:47], v[184:187], v[192:195], v[32:47]
	ds_read_b64_tr_b16 v[192:193], v250 offset:3072
	ds_read_b64_tr_b16 v[194:195], v250 offset:3584
	s_waitcnt lgkmcnt(6)
	v_mfma_f32_32x32x16_bf16 v[48:63], v[184:187], v[196:199], v[48:63]
	ds_read_b64_tr_b16 v[196:197], v250 offset:7168
	ds_read_b64_tr_b16 v[198:199], v250 offset:7680
	s_waitcnt lgkmcnt(6)
	v_mfma_f32_32x32x16_bf16 v[64:79], v[184:187], v[200:203], v[64:79]
	ds_read_b64_tr_b16 v[200:201], v250 offset:11264
	ds_read_b64_tr_b16 v[202:203], v250 offset:11776
	s_waitcnt lgkmcnt(6)
	v_mfma_f32_32x32x16_bf16 v[80:95], v[184:187], v[204:207], v[80:95]
	ds_read_b64_tr_b16 v[204:205], v250 offset:15360
	ds_read_b64_tr_b16 v[206:207], v250 offset:15872
	s_waitcnt lgkmcnt(6)
	v_mfma_f32_32x32x16_bf16 v[32:47], v[188:191], v[192:195], v[32:47]
	s_waitcnt lgkmcnt(4)
	v_mfma_f32_32x32x16_bf16 v[48:63], v[188:191], v[196:199], v[48:63]
	s_waitcnt lgkmcnt(2)
	v_mfma_f32_32x32x16_bf16 v[64:79], v[188:191], v[200:203], v[64:79]
	s_waitcnt lgkmcnt(0)
	v_mfma_f32_32x32x16_bf16 v[80:95], v[188:191], v[204:207], v[80:95]
.Lat_lite2_445:
	s_add_i32 m0, s57, s70
	s_nop 0
	global_load_lds_dwordx4 v238, s[74:75]
	s_add_u32 s74, s74, 0x10000
	s_addc_u32 s75, s75, 0
	s_lshl_b32 s60, s58, 1
	s_add_i32 s60, s60, s71
	s_mov_b32 m0, s60
	s_nop 0
	global_load_lds_dwordx4 v239, s[76:77]
	s_add_u32 s62, s76, 0x80
	s_addc_u32 s63, s77, 0
	s_add_i32 m0, s60, 0x2000
	s_nop 0
	global_load_lds_dwordx4 v239, s[62:63]
	s_add_u32 s76, s76, 0x10000
	s_addc_u32 s77, s77, 0
	s_waitcnt vmcnt(3) lgkmcnt(0)
	s_barrier
	s_mov_b32 s67, s56
	s_mov_b32 s56, s57
	s_mov_b32 s57, s58
	s_mov_b32 s58, s67
	s_add_u32 s46, s46, 1
	s_lshl_b32 s60, s56, 1
	v_add_u32_e32 v250, s60, v245
	s_branch .Lat_next_445
.Lat_lite_859:
	s_cmp_ge_u32 s46, s45
	s_cbranch_scc1 .Lat_drain
	s_cmp_eq_u32 s46, s78
	s_cbranch_scc0 .Lat_lite2_859
	v_add_f32_e32 v247, v247, v128
	v_add_f32_e32 v247, v247, v129
	v_add_f32_e32 v247, v247, v130
	v_add_f32_e32 v247, v247, v131
	v_cvt_pk_bf16_f32 v176, v128, v129
	v_cvt_pk_bf16_f32 v177, v130, v131
	v_add_f32_e32 v247, v247, v132
	v_add_f32_e32 v247, v247, v133
	v_add_f32_e32 v247, v247, v134
	v_add_f32_e32 v247, v247, v135
	v_cvt_pk_bf16_f32 v178, v132, v133
	v_cvt_pk_bf16_f32 v179, v134, v135
	v_add_f32_e32 v247, v247, v136
	v_add_f32_e32 v247, v247, v137
	v_add_f32_e32 v247, v247, v138
	v_add_f32_e32 v247, v247, v139
	v_cvt_pk_bf16_f32 v180, v136, v137
	v_cvt_pk_bf16_f32 v181, v138, v139
	v_add_f32_e32 v247, v247, v140
	v_add_f32_e32 v247, v247, v141
	v_add_f32_e32 v247, v247, v142
	v_add_f32_e32 v247, v247, v143
	v_cvt_pk_bf16_f32 v182, v140, v141
	v_cvt_pk_bf16_f32 v183, v142, v143
	v_add_f32_e32 v247, v247, v144
	v_add_f32_e32 v247, v247, v145
	v_add_f32_e32 v247, v247, v146
	v_add_f32_e32 v247, v247, v147
	v_cvt_pk_bf16_f32 v184, v144, v145
	v_cvt_pk_bf16_f32 v185, v146, v147
	v_add_f32_e32 v247, v247, v148
	v_add_f32_e32 v247, v247, v149
	v_add_f32_e32 v247, v247, v150
	v_add_f32_e32 v247, v247, v151
	v_cvt_pk_bf16_f32 v186, v148, v149
	v_cvt_pk_bf16_f32 v187, v150, v151
	v_add_f32_e32 v247, v247, v152
	v_add_f32_e32 v247, v247, v153
	v_add_f32_e32 v247, v247, v154
	v_add_f32_e32 v247, v247, v155
	v_cvt_pk_bf16_f32 v188, v152, v153
	v_cvt_pk_bf16_f32 v189, v154, v155
	v_add_f32_e32 v247, v247, v156
	v_add_f32_e32 v247, v247, v157
	v_add_f32_e32 v247, v247, v158
	v_add_f32_e32 v247, v247, v159
	v_cvt_pk_bf16_f32 v190, v156, v157
	v_cvt_pk_bf16_f32 v191, v158, v159
	s_lshl_b32 s60, s56, 1
	v_add_u32_e32 v250, s60, v245
	ds_read_b64_tr_b16 v[192:193], v250 offset:0
	ds_read_b64_tr_b16 v[194:195], v250 offset:512
	ds_read_b64_tr_b16 v[196:197], v250 offset:4096
	ds_read_b64_tr_b16 v[198:199], v250 offset:4608
	ds_read_b64_tr_b16 v[200:201], v250 offset:8192
	ds_read_b64_tr_b16 v[202:203], v250 offset:8704
	ds_read_b64_tr_b16 v[204:205], v250 offset:12288
	ds_read_b64_tr_b16 v[206:207], v250 offset:12800
	s_waitcnt lgkmcnt(6)
	v_mfma_f32_32x32x16_bf16 v[32:47], v[176:179], v[192:195], v[32:47]
	ds_read_b64_tr_b16 v[192:193], v250 offset:1024
	ds_read_b64_tr_b16 v[194:195], v250 offset:1536
	s_waitcnt lgkmcnt(6)
	v_mfma_f32_32x32x16_bf16 v[48:63], v[176:179], v[196:199], v[48:63]
	ds_read_b64_tr_b16 v[196:197], v250 offset:5120
	ds_read_b64_tr_b16 v[198:199], v250 offset:5632
	s_waitcnt lgkmcnt(6)
	v_mfma_f32_32x32x16_bf16 v[64:79], v[176:179], v[200:203], v[64:79]
	ds_read_b64_tr_b16 v[200:201], v250 offset:9216
	ds_read_b64_tr_b16 v[202:203], v250 offset:9728
	s_waitcnt lgkmcnt(6)
	v_mfma_f32_32x32x16_bf16 v[80:95], v[176:179], v[204:207], v[80:95]
	ds_read_b64_tr_b16 v[204:205], v250 offset:13312
	ds_read_b64_tr_b16 v[206:207], v250 offset:13824
	s_waitcnt lgkmcnt(6)
	v_mfma_f32_32x32x16_bf16 v[32:47], v[180:183], v[192:195], v[32:47]
	ds_read_b64_tr_b16 v[192:193], v250 offset:2048
	ds_read_b64_tr_b16 v[194:195], v250 offset:2560
	s_waitcnt lgkmcnt(6)
	v_mfma_f32_32x32x16_bf16 v[48:63], v[180:183], v[196:199], v[48:63]
	ds_read_b64_tr_b16 v[196:197], v250 offset:6144
	ds_read_b64_tr_b16 v[198:199], v250 offset:6656
	s_waitcnt lgkmcnt(6)
	v_mfma_f32_32x32x16_bf16 v[64:79], v[180:183], v[200:203], v[64:79]
	ds_read_b64_tr_b16 v[200:201], v250 offset:10240
	ds_read_b64_tr_b16 v[202:203], v250 offset:10752
	s_waitcnt lgkmcnt(6)
	v_mfma_f32_32x32x16_bf16 v[80:95], v[180:183], v[204:207], v[80:95]
	ds_read_b64_tr_b16 v[204:205], v250 offset:14336
	ds_read_b64_tr_b16 v[206:207], v250 offset:14848
	s_waitcnt lgkmcnt(6)
	v_mfma_f32_32x32x16_bf16 v[32:47], v[184:187], v[192:195], v[32:47]
	ds_read_b64_tr_b16 v[192:193], v250 offset:3072
	ds_read_b64_tr_b16 v[194:195], v250 offset:3584
	s_waitcnt lgkmcnt(6)
	v_mfma_f32_32x32x16_bf16 v[48:63], v[184:187], v[196:199], v[48:63]
	ds_read_b64_tr_b16 v[196:197], v250 offset:7168
	ds_read_b64_tr_b16 v[198:199], v250 offset:7680
	s_waitcnt lgkmcnt(6)
	v_mfma_f32_32x32x16_bf16 v[64:79], v[184:187], v[200:203], v[64:79]
	ds_read_b64_tr_b16 v[200:201], v250 offset:11264
	ds_read_b64_tr_b16 v[202:203], v250 offset:11776
	s_waitcnt lgkmcnt(6)
	v_mfma_f32_32x32x16_bf16 v[80:95], v[184:187], v[204:207], v[80:95]
	ds_read_b64_tr_b16 v[204:205], v250 offset:15360
	ds_read_b64_tr_b16 v[206:207], v250 offset:15872
	s_waitcnt lgkmcnt(6)
	v_mfma_f32_32x32x16_bf16 v[32:47], v[188:191], v[192:195], v[32:47]
	s_waitcnt lgkmcnt(4)
	v_mfma_f32_32x32x16_bf16 v[48:63], v[188:191], v[196:199], v[48:63]
	s_waitcnt lgkmcnt(2)
	v_mfma_f32_32x32x16_bf16 v[64:79], v[188:191], v[200:203], v[64:79]
	s_waitcnt lgkmcnt(0)
	v_mfma_f32_32x32x16_bf16 v[80:95], v[188:191], v[204:207], v[80:95]
